# fold table + gate clamp trim + rope-load waits moved in front of the join labels (context q/k tiles no longer drain their stores)
# speedup vs baseline: 1.0054x; 1.0054x over previous
.LBB0_1368:
	s_andn2_b64 vcc, exec, s[44:45]
	s_mov_b32 s78, 0x3b800000
	s_cbranch_vccnz .LBB0_1370
	v_mov_b32_e32 v2, v221
	s_nop 0
	v_lshlrev_b32_e32 v2, 7, v2
	v_and_b32_e32 v2, 0x1ff80, v2
	v_lshl_add_u64 v[132:133], v[186:187], 0, v[2:3]
	v_lshl_add_u64 v[134:135], v[184:185], 0, v[2:3]
	v_mov_b32_e32 v2, v220
	global_load_dwordx4 v[160:163], v[132:133], off
	global_load_dwordx4 v[156:159], v[134:135], off
	s_nop 0
	v_lshlrev_b32_e32 v2, 7, v2
	v_and_b32_e32 v2, 0x1ff80, v2
	v_lshl_add_u64 v[132:133], v[186:187], 0, v[2:3]
	v_lshl_add_u64 v[134:135], v[184:185], 0, v[2:3]
	v_mov_b32_e32 v2, v195
	global_load_dwordx4 v[152:155], v[132:133], off
	global_load_dwordx4 v[148:151], v[134:135], off
	s_nop 0
	v_lshlrev_b32_e32 v2, 7, v2
	v_and_b32_e32 v2, 0x1ff80, v2
	v_lshl_add_u64 v[132:133], v[186:187], 0, v[2:3]
	v_lshl_add_u64 v[134:135], v[184:185], 0, v[2:3]
	v_mov_b32_e32 v2, v194
	global_load_dwordx4 v[136:139], v[132:133], off
	s_nop 0
	global_load_dwordx4 v[132:135], v[134:135], off
	s_nop 0
	v_lshlrev_b32_e32 v2, 7, v2
	v_and_b32_e32 v2, 0x1ff80, v2
	v_lshl_add_u64 v[140:141], v[186:187], 0, v[2:3]
	v_lshl_add_u64 v[142:143], v[184:185], 0, v[2:3]
	global_load_dwordx4 v[144:147], v[140:141], off
	s_nop 0
	global_load_dwordx4 v[140:143], v[142:143], off
	s_waitcnt vmcnt(0)
.LBB0_1370:
	v_pk_mul_f32 v[164:165], v[158:159], v[62:63]
	v_pk_mul_f32 v[166:167], v[156:157], v[60:61]
	v_pk_fma_f32 v[168:169], v[162:163], v[66:67], v[164:165] neg_lo:[0,0,1] neg_hi:[0,0,1]
	v_pk_fma_f32 v[164:165], v[160:161], v[64:65], v[166:167] neg_lo:[0,0,1] neg_hi:[0,0,1]
	v_pk_mul_f32 v[166:167], v[162:163], v[62:63]
	v_pk_mul_f32 v[170:171], v[160:161], v[60:61]
	v_pk_fma_f32 v[174:175], v[158:159], v[66:67], v[166:167]
	v_pk_fma_f32 v[170:171], v[156:157], v[64:65], v[170:171]
	v_mov_b32_e32 v172, v221
	v_cndmask_b32_e64 v165, v65, v165, s[76:77]
	v_cndmask_b32_e64 v164, v64, v164, s[76:77]
	v_cndmask_b32_e64 v167, v67, v169, s[76:77]
	v_cndmask_b32_e64 v166, v66, v168, s[76:77]
	v_cndmask_b32_e64 v169, v61, v171, s[76:77]
	v_cndmask_b32_e64 v168, v60, v170, s[76:77]
	v_cndmask_b32_e64 v171, v63, v175, s[76:77]
	v_cndmask_b32_e64 v170, v62, v174, s[76:77]
	s_mov_b64 s[44:45], -1
	s_and_b64 vcc, exec, s[4:5]
	s_cbranch_vccz .LBB0_1372
	v_pk_mul_f32 v[176:177], v[166:167], s[34:35] op_sel_hi:[1,0]
	v_pk_mul_f32 v[174:175], v[164:165], s[34:35] op_sel_hi:[1,0]
	v_pk_mul_f32 v[236:237], v[170:171], s[34:35] op_sel_hi:[1,0]
	v_cvt_pk_bf16_f32 v174, v174, v175
	v_cvt_pk_bf16_f32 v175, v176, v177
	v_pk_mul_f32 v[176:177], v[168:169], s[34:35] op_sel_hi:[1,0]
	v_lshl_add_u32 v2, v172, 9, v234
	v_cvt_pk_bf16_f32 v176, v176, v177
	v_cvt_pk_bf16_f32 v177, v236, v237
	v_lshl_add_u64 v[178:179], v[2:3], 1, s[48:49]
	v_permlane16_swap_b32_e32 v174, v176
	v_permlane16_swap_b32_e32 v175, v177
	global_store_dwordx4 v[178:179], v[174:177], off
	s_mov_b64 s[44:45], 0

.LBB0_1485:
	s_andn2_b64 vcc, exec, s[4:5]
	s_cbranch_vccnz .LBB0_1537
	s_and_b64 vcc, exec, s[42:43]
	s_cbranch_vccnz .LBB0_1488
	v_mov_b32_e32 v0, v225
	s_nop 0
	v_lshlrev_b32_e32 v0, 7, v0
	v_and_b32_e32 v2, 0x1ff80, v0
	v_lshl_add_u64 v[132:133], v[186:187], 0, v[2:3]
	v_mov_b32_e32 v0, v224
	v_lshl_add_u64 v[134:135], v[184:185], 0, v[2:3]
	global_load_dwordx4 v[160:163], v[132:133], off
	global_load_dwordx4 v[156:159], v[134:135], off
	s_nop 0
	v_lshlrev_b32_e32 v0, 7, v0
	v_and_b32_e32 v2, 0x1ff80, v0
	v_lshl_add_u64 v[132:133], v[186:187], 0, v[2:3]
	v_mov_b32_e32 v0, v223
	v_lshl_add_u64 v[134:135], v[184:185], 0, v[2:3]
	global_load_dwordx4 v[152:155], v[132:133], off
	global_load_dwordx4 v[148:151], v[134:135], off
	s_nop 0
	v_lshlrev_b32_e32 v0, 7, v0
	v_and_b32_e32 v2, 0x1ff80, v0
	v_lshl_add_u64 v[132:133], v[186:187], 0, v[2:3]
	v_lshl_add_u64 v[134:135], v[184:185], 0, v[2:3]
	v_mov_b32_e32 v0, v222
	global_load_dwordx4 v[136:139], v[132:133], off
	s_nop 0
	global_load_dwordx4 v[132:135], v[134:135], off
	s_nop 0
	v_lshlrev_b32_e32 v0, 7, v0
	v_and_b32_e32 v2, 0x1ff80, v0
	v_lshl_add_u64 v[140:141], v[186:187], 0, v[2:3]
	v_lshl_add_u64 v[142:143], v[184:185], 0, v[2:3]
	global_load_dwordx4 v[144:147], v[140:141], off
	s_nop 0
	global_load_dwordx4 v[140:143], v[142:143], off
	s_waitcnt vmcnt(0)
.LBB0_1488:
	s_cmpk_gt_i32 s80, 0x1ff
	s_cselect_b64 s[4:5], -1, 0
	s_add_i32 s20, s67, 0xfffffe80
	s_cmpk_lt_i32 s80, 0x200
	s_cselect_b64 s[42:43], -1, 0
	s_and_b64 vcc, s[42:43], exec
	v_pk_mul_f32 v[166:167], v[156:157], v[116:117]
	s_cselect_b32 s20, s80, s20
	v_readlane_b32 s42, v255, 6
	v_pk_mul_f32 v[164:165], v[158:159], v[118:119]
	v_pk_fma_f32 v[168:169], v[160:161], v[120:121], v[166:167] neg_lo:[0,0,1] neg_hi:[0,0,1]
	v_pk_mul_f32 v[166:167], v[162:163], v[118:119]
	v_pk_mul_f32 v[170:171], v[160:161], v[116:117]
	s_or_b32 s20, s20, s42
	v_pk_fma_f32 v[164:165], v[162:163], v[122:123], v[164:165] neg_lo:[0,0,1] neg_hi:[0,0,1]
	v_pk_fma_f32 v[176:177], v[158:159], v[122:123], v[166:167]
	v_pk_fma_f32 v[178:179], v[156:157], v[120:121], v[170:171]
	v_cndmask_b32_e64 v0, 0, 1, s[40:41]
	v_add_u32_e32 v172, s20, v230
	v_add_u32_e32 v173, s20, v231
	v_mov_b32_e32 v174, v225
	v_cndmask_b32_e64 v167, v123, v165, s[76:77]
	v_cndmask_b32_e64 v166, v122, v164, s[76:77]
	v_cndmask_b32_e64 v165, v121, v169, s[76:77]
	v_cndmask_b32_e64 v164, v120, v168, s[76:77]
	v_cndmask_b32_e64 v171, v119, v177, s[76:77]
	v_cndmask_b32_e64 v170, v118, v176, s[76:77]
	v_cndmask_b32_e64 v169, v117, v179, s[76:77]
	v_cndmask_b32_e64 v168, v116, v178, s[76:77]
	s_mov_b64 s[44:45], -1
	v_cmp_ne_u32_e64 s[42:43], 1, v0
	s_cbranch_vccnz .LBB0_1492
	v_lshlrev_b32_e32 v175, 7, v174
	v_add_u32_e32 v2, v175, v172
	v_cvt_pk_bf16_f32 v176, v164, v165
	v_cvt_pk_bf16_f32 v177, v166, v167
	v_cvt_pk_bf16_f32 v178, v168, v169
	v_cvt_pk_bf16_f32 v179, v170, v171
	v_lshl_add_u64 v[228:229], v[2:3], 1, s[50:51]
	v_permlane16_swap_b32_e32 v176, v178
	v_permlane16_swap_b32_e32 v177, v179
	s_and_b64 vcc, exec, s[42:43]
	global_store_dwordx4 v[228:229], v[176:179], off
	s_cbranch_vccnz .LBB0_1491
	v_lshrrev_b32_e32 v0, 7, v174
	v_and_b32_e32 v0, 0x1fffe, v0
	v_readlane_b32 s2, v254, 57
	v_and_b32_e32 v1, 0x7f80, v175
	s_nop 0
	v_add_lshl_u32 v0, v0, s2, 15
	v_add3_u32 v2, v1, v173, v0
	v_lshl_add_u64 v[176:177], v[2:3], 2, s[26:27]
	global_store_dwordx4 v[176:177], v[164:167], off nt
	global_store_dwordx4 v[176:177], v[168:171], off offset:128 nt

.LBB0_1512:
	v_mov_b32_e32 v0, v221
	s_nop 0
	v_lshlrev_b32_e32 v0, 7, v0
	v_and_b32_e32 v2, 0x1ff80, v0
	v_lshl_add_u64 v[132:133], v[186:187], 0, v[2:3]
	v_mov_b32_e32 v0, v220
	v_lshl_add_u64 v[134:135], v[184:185], 0, v[2:3]
	global_load_dwordx4 v[160:163], v[132:133], off
	global_load_dwordx4 v[156:159], v[134:135], off
	s_nop 0
	v_lshlrev_b32_e32 v0, 7, v0
	v_and_b32_e32 v2, 0x1ff80, v0
	v_lshl_add_u64 v[132:133], v[186:187], 0, v[2:3]
	v_mov_b32_e32 v0, v195
	v_lshl_add_u64 v[134:135], v[184:185], 0, v[2:3]
	global_load_dwordx4 v[152:155], v[132:133], off
	global_load_dwordx4 v[148:151], v[134:135], off
	s_nop 0
	v_lshlrev_b32_e32 v0, 7, v0
	v_and_b32_e32 v2, 0x1ff80, v0
	v_lshl_add_u64 v[132:133], v[186:187], 0, v[2:3]
	v_lshl_add_u64 v[134:135], v[184:185], 0, v[2:3]
	v_mov_b32_e32 v0, v194
	global_load_dwordx4 v[136:139], v[132:133], off
	s_nop 0
	global_load_dwordx4 v[132:135], v[134:135], off
	s_nop 0
	v_lshlrev_b32_e32 v0, 7, v0
	v_and_b32_e32 v2, 0x1ff80, v0
	v_lshl_add_u64 v[140:141], v[186:187], 0, v[2:3]
	v_lshl_add_u64 v[142:143], v[184:185], 0, v[2:3]
	global_load_dwordx4 v[144:147], v[140:141], off
	s_nop 0
	global_load_dwordx4 v[140:143], v[142:143], off
	s_waitcnt vmcnt(0)
.LBB0_1513:
	v_pk_mul_f32 v[166:167], v[158:159], v[54:55]
	v_pk_mul_f32 v[168:169], v[156:157], v[52:53]
	v_pk_fma_f32 v[166:167], v[162:163], v[58:59], v[166:167] neg_lo:[0,0,1] neg_hi:[0,0,1]
	v_pk_fma_f32 v[168:169], v[160:161], v[56:57], v[168:169] neg_lo:[0,0,1] neg_hi:[0,0,1]
	v_pk_mul_f32 v[162:163], v[162:163], v[54:55]
	v_pk_mul_f32 v[160:161], v[160:161], v[52:53]
	v_pk_fma_f32 v[162:163], v[158:159], v[58:59], v[162:163]
	v_pk_fma_f32 v[160:161], v[156:157], v[56:57], v[160:161]
	v_mov_b32_e32 v164, v221
	v_cndmask_b32_e64 v157, v57, v169, s[76:77]
	v_cndmask_b32_e64 v156, v56, v168, s[76:77]
	v_cndmask_b32_e64 v159, v59, v167, s[76:77]
	v_cndmask_b32_e64 v158, v58, v166, s[76:77]
	v_cndmask_b32_e64 v161, v53, v161, s[76:77]
	v_cndmask_b32_e64 v160, v52, v160, s[76:77]
	v_cndmask_b32_e64 v163, v55, v163, s[76:77]
	v_cndmask_b32_e64 v162, v54, v162, s[76:77]
	s_and_b64 vcc, exec, s[44:45]
	s_mov_b64 s[4:5], -1
	s_cbranch_vccnz .LBB0_1517
	v_lshlrev_b32_e32 v165, 7, v164
	v_add_u32_e32 v2, v165, v172
	v_cvt_pk_bf16_f32 v166, v156, v157
	v_cvt_pk_bf16_f32 v167, v158, v159
	v_cvt_pk_bf16_f32 v168, v160, v161
	v_cvt_pk_bf16_f32 v169, v162, v163
	v_lshl_add_u64 v[170:171], v[2:3], 1, s[50:51]
	v_permlane16_swap_b32_e32 v166, v168
	v_permlane16_swap_b32_e32 v167, v169
	s_and_b64 vcc, exec, s[42:43]
	global_store_dwordx4 v[170:171], v[166:169], off
	s_cbranch_vccnz .LBB0_1516
	v_lshrrev_b32_e32 v0, 7, v164
	v_and_b32_e32 v0, 0x1fffe, v0
	v_readlane_b32 s2, v254, 57
	v_and_b32_e32 v1, 0x7f80, v165
	s_nop 0
	v_add_lshl_u32 v0, v0, s2, 15
	v_add3_u32 v2, v1, v173, v0
	v_lshl_add_u64 v[166:167], v[2:3], 2, s[26:27]
	global_store_dwordx4 v[166:167], v[156:159], off nt
	global_store_dwordx4 v[166:167], v[160:163], off offset:128 nt
